# hot loop heads aligned to 128 bytes instead of 64
# baseline (speedup 1.0000x reference)
; template <class Epi>
; __device__ __forceinline__ void gemm_tile(const bf16_t* __restrict__ A, const bf16_t* __restrict__ Bt, int K, int row0, int col0, const Epi& epi, char* smem,
;                                           bool prefetched, bool nvalid, int nrow0, int ncol0) {
;     ...
;     for (int kt = 0; kt < nk; ++kt) {
;         const int cur = kt & 1;
;         if (kt + 1 < nk) GLDS_STAGE(cur ^ 1, pA, pB, kt + 1);
;         const char* cb = smem + cur * 2 * TILE_B;
; #pragma unroll
;         for (int ks = 0; ks < 2; ++ks) {
;             bf16x8 a[4], b[4];
; #pragma unroll
;             for (int m = 0; m < 4; ++m) a[m] = *(const bf16x8*)(cb + offA[m][ks]);
; #pragma unroll
;             for (int n = 0; n < 4; ++n) b[n] = *(const bf16x8*)(cb + offB[n][ks]);
.LBB0_154:
	v_readfirstlane_b32 s98, v64
	v_readfirstlane_b32 s99, v65
	v_readfirstlane_b32 s10, v66
	v_readfirstlane_b32 s100, v72
	v_readfirstlane_b32 s101, v73
	v_readfirstlane_b32 s13, v149
	s_nop 3
	s_sub_u32 s14, s10, s98
	s_and_b32 s98, s98, 0xffffff80
	s_and_b32 s100, s100, 0xffffff80
	s_nop 1
	v_subrev_u32_e32 v254, s98, v64
	v_subrev_u32_e32 v255, s100, v72
	s_add_i32 s12, s13, 0x8000
	s_mov_b32 m0, s12
	s_nop 0
	global_load_lds_dwordx4 v254, s[98:99]
	s_add_i32 m0, s12, 0x1000
	s_add_u32 s10, s98, s14
	s_addc_u32 s11, s99, 0
	global_load_lds_dwordx4 v254, s[10:11]
	s_add_i32 m0, s12, 0x2000
	s_add_u32 s10, s10, s14
	s_addc_u32 s11, s11, 0
	global_load_lds_dwordx4 v254, s[10:11]
	s_add_i32 m0, s12, 0x3000
	s_add_u32 s10, s10, s14
	s_addc_u32 s11, s11, 0
	global_load_lds_dwordx4 v254, s[10:11]
	s_add_u32 s98, s98, 0x80
	s_addc_u32 s99, s99, 0
	ds_read_b128 v[182:185], v139
	ds_read_b128 v[64:67], v142 offset:16384
	ds_read_b128 v[68:71], v142 offset:16896
	ds_read_b128 v[72:75], v142 offset:20480
	ds_read_b128 v[76:79], v142 offset:20992
	ds_read_b128 v[186:189], v139 offset:2048
	ds_read_b128 v[246:249], v139 offset:4096
	ds_read_b128 v[250:253], v139 offset:6144
	s_setprio 1
	.p2alignl 7, 3212836864

; template <class Epi>
; __device__ __forceinline__ void gemm_tile(const bf16_t* __restrict__ A, const bf16_t* __restrict__ Bt, int K, int row0, int col0, const Epi& epi, char* smem,
;                                           bool prefetched, bool nvalid, int nrow0, int ncol0) {
;     ...
;     for (int kt = 0; kt < nk; ++kt) {
;         const int cur = kt & 1;
;         if (kt + 1 < nk) GLDS_STAGE(cur ^ 1, pA, pB, kt + 1);
;         const char* cb = smem + cur * 2 * TILE_B;
; #pragma unroll
;         for (int ks = 0; ks < 2; ++ks) {
;             bf16x8 a[4], b[4];
; #pragma unroll
;             for (int m = 0; m < 4; ++m) a[m] = *(const bf16x8*)(cb + offA[m][ks]);
; #pragma unroll
;             for (int n = 0; n < 4; ++n) b[n] = *(const bf16x8*)(cb + offB[n][ks]);
.LBB0_197:
	v_readfirstlane_b32 s98, v106
	v_readfirstlane_b32 s99, v107
	v_readfirstlane_b32 s8, v108
	v_readfirstlane_b32 s100, v120
	v_readfirstlane_b32 s101, v121
	v_readfirstlane_b32 s11, v149
	s_nop 3
	s_sub_u32 s15, s8, s98
	s_and_b32 s98, s98, 0xffffff80
	s_and_b32 s100, s100, 0xffffff80
	s_nop 1
	v_subrev_u32_e32 v254, s98, v106
	v_subrev_u32_e32 v255, s100, v120
	s_add_i32 s10, s11, 0x8000
	s_mov_b32 m0, s10
	s_nop 0
	global_load_lds_dwordx4 v254, s[98:99]
	s_add_i32 m0, s10, 0x1000
	s_add_u32 s8, s98, s15
	s_addc_u32 s9, s99, 0
	global_load_lds_dwordx4 v254, s[8:9]
	s_add_i32 m0, s10, 0x2000
	s_add_u32 s8, s8, s15
	s_addc_u32 s9, s9, 0
	global_load_lds_dwordx4 v254, s[8:9]
	s_add_i32 m0, s10, 0x3000
	s_add_u32 s8, s8, s15
	s_addc_u32 s9, s9, 0
	global_load_lds_dwordx4 v254, s[8:9]
	s_add_u32 s98, s98, 0x80
	s_addc_u32 s99, s99, 0
	ds_read_b128 v[188:191], v117
	ds_read_b128 v[106:109], v130 offset:16384
	ds_read_b128 v[118:121], v130 offset:16896
	ds_read_b128 v[122:125], v130 offset:20480
	ds_read_b128 v[168:171], v130 offset:20992
	ds_read_b128 v[192:195], v117 offset:2048
	ds_read_b128 v[196:199], v117 offset:4096
	ds_read_b128 v[246:249], v117 offset:6144
	s_setprio 1
	.p2alignl 7, 3212836864

; __device__ __forceinline__ unsigned cvt_pk_bf16(float lo, float hi) { const f32x2_t f = {lo, hi}; return __builtin_bit_cast(unsigned, __builtin_convertvector(f, bf16x2_t)); }
; __device__ __forceinline__ float bf_lo(unsigned u) { return __uint_as_float(u << 16); }
; __device__ __forceinline__ float bf_hi(unsigned u) { return __uint_as_float(u & 0xffff0000u); }
; __device__ __forceinline__ f32x4 mfma16(bf16x8 a, bf16x8 b, f32x4 c) { return __builtin_amdgcn_mfma_f32_16x16x32_bf16(a, b, c, 0, 0, 0); }
; __device__ __forceinline__ void compress_task(const Params& p, int task, char* smem) {
;     ...
; #pragma unroll 2
;     for (int kq = 0; kq < 16; ++kq) {
;         const int kk = w * 16 + kq, l = kk >> 1, d = (kk & 1) * 32 + fq * 8;
;         int tok = 16 * n + l; tok = tok < S ? tok : S - 1;
;         const u32x4 raw = *(const u32x4*)(src + (size_t)tok * LDA + d);
;         const float* pp = pos + l * 64 + d;
;         const f32x4 p0 = *(const f32x4*)pp, p1 = *(const f32x4*)(pp + 4);
;         u32x4 ap;
;         ap.x = cvt_pk_bf16(bf_lo(raw.x) + p0[0], bf_hi(raw.x) + p0[1]);
;         ap.y = cvt_pk_bf16(bf_lo(raw.y) + p0[2], bf_hi(raw.y) + p0[3]);
;         ap.z = cvt_pk_bf16(bf_lo(raw.z) + p1[0], bf_hi(raw.z) + p1[1]);
;         ap.w = cvt_pk_bf16(bf_lo(raw.w) + p1[2], bf_hi(raw.w) + p1[3]);
;         const bf16x8 a = __builtin_bit_cast(bf16x8, ap);
; #pragma unroll
;         for (int nt = 0; nt < 16; ++nt) {
;             const bf16x8 bw = *(const bf16x8*)(w1t + (size_t)(nt * 16 + fr) * 2048 + kk * 32 + fq * 8);
;             acc[nt] = mfma16(bw, a, acc[nt]);
;         }
.LBB0_250:
	v_readfirstlane_b32 s98, v92
	v_readfirstlane_b32 s99, v93
	v_readfirstlane_b32 s100, v114
	s_mov_b32 s18, 0
	v_mbcnt_lo_u32_b32 v129, -1, 0
	v_mbcnt_hi_u32_b32 v129, -1, v129
	v_lshlrev_b32_e32 v129, 4, v129
	s_nop 3
	s_lshr_b32 s100, s100, 6
	s_lshl_b32 s101, s100, 10
	s_lshl_b32 s100, s100, 14
	s_sub_u32 s98, s98, s101
	s_subb_u32 s99, s99, 0
	s_add_u32 s98, s98, s100
	s_addc_u32 s99, s99, 0
	v_min_u32_e32 v117, 0xfff, v89
	v_mul_u32_u24_e32 v117, 0x880, v117
	v_lshlrev_b32_e32 v64, 1, v117
	s_nop 0
	v_lshl_add_u64 v[126:127], v[90:91], 0, v[64:65]
	global_load_dword v131, v[126:127], off
	v_add_u32_e32 v117, 1, v89
	v_min_u32_e32 v117, 0xfff, v117
	v_mul_u32_u24_e32 v117, 0x880, v117
	v_lshlrev_b32_e32 v64, 1, v117
	s_nop 0
	v_lshl_add_u64 v[126:127], v[90:91], 0, v[64:65]
	global_load_dword v131, v[126:127], off
	v_add_u32_e32 v117, 2, v89
	v_min_u32_e32 v117, 0xfff, v117
	v_mul_u32_u24_e32 v117, 0x880, v117
	v_lshlrev_b32_e32 v64, 1, v117
	s_nop 0
	v_lshl_add_u64 v[126:127], v[90:91], 0, v[64:65]
	global_load_dword v131, v[126:127], off
	v_add_u32_e32 v117, 3, v89
	v_min_u32_e32 v117, 0xfff, v117
	v_mul_u32_u24_e32 v117, 0x880, v117
	v_lshlrev_b32_e32 v64, 1, v117
	s_nop 0
	v_lshl_add_u64 v[126:127], v[90:91], 0, v[64:65]
	global_load_dword v131, v[126:127], off
	v_add_u32_e32 v117, 4, v89
	v_min_u32_e32 v117, 0xfff, v117
	v_mul_u32_u24_e32 v117, 0x880, v117
	v_lshlrev_b32_e32 v64, 1, v117
	s_nop 0
	v_lshl_add_u64 v[126:127], v[90:91], 0, v[64:65]
	global_load_dword v131, v[126:127], off
	v_add_u32_e32 v117, 5, v89
	v_min_u32_e32 v117, 0xfff, v117
	v_mul_u32_u24_e32 v117, 0x880, v117
	v_lshlrev_b32_e32 v64, 1, v117
	s_nop 0
	v_lshl_add_u64 v[126:127], v[90:91], 0, v[64:65]
	global_load_dword v131, v[126:127], off
	v_add_u32_e32 v117, 6, v89
	v_min_u32_e32 v117, 0xfff, v117
	v_mul_u32_u24_e32 v117, 0x880, v117
	v_lshlrev_b32_e32 v64, 1, v117
	s_nop 0
	v_lshl_add_u64 v[126:127], v[90:91], 0, v[64:65]
	global_load_dword v131, v[126:127], off
	v_add_u32_e32 v117, 7, v89
	v_min_u32_e32 v117, 0xfff, v117
	v_mul_u32_u24_e32 v117, 0x880, v117
	v_lshlrev_b32_e32 v64, 1, v117
	s_nop 0
	v_lshl_add_u64 v[126:127], v[90:91], 0, v[64:65]
	global_load_dword v131, v[126:127], off
	v_lshl_add_u64 v[110:111], v[96:97], 0, v[86:87]
	v_min_u32_e32 v117, 0xfff, v89
	v_mul_u32_u24_e32 v117, 0x880, v117
	global_load_dwordx4 v[166:169], v[110:111], off
	global_load_dwordx4 v[170:173], v[110:111], off offset:16
	v_lshlrev_b32_e32 v64, 1, v117
	s_nop 0
	v_lshl_add_u64 v[126:127], v[90:91], 0, v[64:65]
	global_load_dwordx4 v[162:165], v[126:127], off
	v_lshl_add_u64 v[110:111], v[94:95], 0, v[86:87]
	v_min_u32_e32 v117, 0xfff, v105
	v_mul_u32_u24_e32 v117, 0x880, v117
	global_load_dwordx4 v[246:249], v[110:111], off offset:128
	global_load_dwordx4 v[250:253], v[110:111], off offset:144
	v_lshlrev_b32_e32 v64, 1, v117
	s_nop 0
	v_lshl_add_u64 v[126:127], v[90:91], 0, v[64:65]
	global_load_dwordx4 v[174:177], v[126:127], off offset:64
	global_load_dwordx4 v[180:183], v129, s[98:99]
	s_add_u32 s100, s98, 0x10000
	s_addc_u32 s101, s99, 0
	global_load_dwordx4 v[184:187], v129, s[100:101]
	s_add_u32 s100, s98, 0x400
	s_addc_u32 s101, s99, 0
	global_load_dwordx4 v[188:191], v129, s[100:101]
	s_add_u32 s100, s98, 0x10400
	s_addc_u32 s101, s99, 0
	global_load_dwordx4 v[192:195], v129, s[100:101]
	s_add_u32 s100, s98, 0x20000
	s_addc_u32 s101, s99, 0
	global_load_dwordx4 v[196:199], v129, s[100:101]
	s_add_u32 s100, s98, 0x30000
	s_addc_u32 s101, s99, 0
	global_load_dwordx4 v[200:203], v129, s[100:101]
	s_add_u32 s100, s98, 0x20400
	s_addc_u32 s101, s99, 0
	global_load_dwordx4 v[204:207], v129, s[100:101]
	s_add_u32 s100, s98, 0x30400
	s_addc_u32 s101, s99, 0
	global_load_dwordx4 v[208:211], v129, s[100:101]
	s_add_u32 s100, s98, 0x40000
	s_addc_u32 s101, s99, 0
	global_load_dwordx4 v[212:215], v129, s[100:101]
	s_add_u32 s100, s98, 0x50000
	s_addc_u32 s101, s99, 0
	global_load_dwordx4 v[216:219], v129, s[100:101]
	s_add_u32 s100, s98, 0x40400
	s_addc_u32 s101, s99, 0
	global_load_dwordx4 v[220:223], v129, s[100:101]
	s_add_u32 s100, s98, 0x50400
	s_addc_u32 s101, s99, 0
	global_load_dwordx4 v[224:227], v129, s[100:101]
	s_add_u32 s100, s98, 0x60000
	s_addc_u32 s101, s99, 0
	global_load_dwordx4 v[228:231], v129, s[100:101]
	s_add_u32 s100, s98, 0x70000
	s_addc_u32 s101, s99, 0
	global_load_dwordx4 v[232:235], v129, s[100:101]
	s_add_u32 s100, s98, 0x60400
	s_addc_u32 s101, s99, 0
	global_load_dwordx4 v[236:239], v129, s[100:101]
	s_add_u32 s100, s98, 0x70400
	s_addc_u32 s101, s99, 0
	global_load_dwordx4 v[240:243], v129, s[100:101]
	.p2alignl 7, 3212836864

; __device__ __forceinline__ f32x4 zero4() { return (f32x4){0.f, 0.f, 0.f, 0.f}; }
; template <int KW, int VD, bool SEL> ...
;     ...
;     if (!tiles) return;
;     int koff[NKI], voff[NVI];
; #pragma unroll
;     for (int i = 0; i < NKI; ++i) {
;         const int row = (w + 4 * i) * KRPI + lane / KCPR, cp = lane % KCPR;
;         const int f = (KW == 64) ? (((row >> 1) & 1) | (((row >> 3) & 1) << 1) | (((row >> 4) & 1) << 2)) : ((row & 3) | (((row >> 3) & 3) << 2));
;         koff[i] = row * ldk + (cp ^ f) * 8;
;     }
; #pragma unroll
;     for (int i = 0; i < NVI; ++i) {
;         const int row = (w + 4 * i) * 8 + (lane >> 3), cp = lane & 7;
;         voff[i] = row * S + (cp ^ ((row >> 1) & 7)) * 8;
;     }
;     ...
;     int j = __ffsll((long long)tiles) - 1; tiles &= tiles - 1;
;     FL_ISSUE(0, j);
;     asm volatile("s_waitcnt vmcnt(0)" ::: "memory");
;     __syncthreads();
;     int cur = 0;
;     const int kswz = (KW == 64) ? ((fr >> 1) & 7) : fr;
;     const int vswz = (fr >> 1) & 7;
;     while (true) {
; __device__ __forceinline__ void nsa_tile(const Params& p, int qb, int bg, char* smem) {
;     ...
;     u64 ormask = 0;
; #pragma unroll 4
;     for (int i = 0; i < 32; ++i) ormask |= selmask[i];
;     ormask = ((u64)__builtin_amdgcn_readfirstlane((unsigned)(ormask >> 32)) << 32) | (u64)__builtin_amdgcn_readfirstlane((unsigned)ormask);
;     const u64 selm[2] = {~0ull, ~0ull};
;     const int cur0 = t0 >> 6;
;     float* park = part;
;     __syncthreads();
; #pragma unroll
;     for (int qt = 0; qt < 2; ++qt)
; #pragma unroll
;         for (int dt = 0; dt < 4; ++dt)
;             ((f32x4*)park)[(qt * 4 + dt) * 256 + tid] = outacc[qt][dt];
;     {
;         f32x4 O[2][4];
; #pragma unroll
;         for (int qt = 0; qt < 2; ++qt)
; #pragma unroll
;             for (int dt = 0; dt < 4; ++dt) O[qt][dt] = zero4();
;         float mr[2] = {-1e30f, -1e30f}, lr[2] = {0.f, 0.f};
;         const int lo[2] = {-1, -1};
;         flash_branch<64, 64, true>(ormask, projA + (size_t)b * S * LDA + 1536 + g * 64, LDA, projVT + ((size_t)b * 512 + g * 64) * S, 0,
;                                    qf, O, mr, lr, tpos, selm, lo, t0, -1, smem);
.LBB0_366:
	s_add_i32 s1, s0, 0x11000
	s_add_i32 s2, s0, 0x11010
	v_mov_b32_e32 v3, s1
	v_mov_b32_e32 v58, s2
	ds_read_b128 v[54:57], v3
	ds_read_b128 v[58:61], v58
	s_add_i32 s0, s0, 32
	s_cmpk_eq_i32 s0, 0x100
	s_waitcnt lgkmcnt(1)
	v_or_b32_e32 v3, v54, v52
	v_or_b32_e32 v52, v55, v53
	v_or_b32_e32 v3, v56, v3
	v_or_b32_e32 v52, v57, v52
	s_waitcnt lgkmcnt(0)
	v_or_b32_e32 v3, v58, v3
	v_or_b32_e32 v53, v59, v52
	v_or_b32_e32 v52, v60, v3
	v_or_b32_e32 v53, v61, v53
	s_cbranch_scc0 .LBB0_366
	v_readlane_b32 s16, v244, 17
	v_readfirstlane_b32 s1, v53
	v_readfirstlane_b32 s0, v52
	v_readlane_b32 s17, v244, 18
	s_mov_b32 s2, s17
	s_mov_b32 s3, s1
	s_bfe_i64 s[0:1], s[0:1], 0x200000
	v_readlane_b32 s8, v244, 13
	s_or_b64 s[0:1], s[0:1], s[2:3]
	s_mul_i32 s2, s8, 0x1100000
	v_readlane_b32 s4, v245, 55
	v_readlane_b32 s5, v245, 56
	s_add_u32 s2, s4, s2
	s_addc_u32 s3, s5, 0
	v_readlane_b32 s5, v244, 12
	s_lshl_b32 s4, s5, 7
	s_add_u32 s6, s2, s4
	s_addc_u32 s7, s3, 0
	s_lshl_b32 s2, s8, 22
	s_lshl_b32 s3, s5, 19
	v_readlane_b32 s4, v245, 57
	s_add_u32 s2, s4, s2
	v_readlane_b32 s4, v245, 58
	s_addc_u32 s4, s4, 0
	s_add_u32 s8, s2, s3
	v_lshlrev_b32_e32 v122, 4, v76
	s_addc_u32 s9, s4, 0
	v_readlane_b32 s52, v244, 3
	v_pk_mul_f32 v[38:39], v[0:1], v[38:39] op_sel_hi:[0,1]
	v_pk_mul_f32 v[36:37], v[0:1], v[36:37] op_sel_hi:[0,1]
	v_pk_mul_f32 v[46:47], v[2:3], v[46:47] op_sel_hi:[0,1]
	v_pk_mul_f32 v[44:45], v[2:3], v[44:45] op_sel_hi:[0,1]
	v_pk_mul_f32 v[34:35], v[0:1], v[34:35] op_sel_hi:[0,1]
	v_pk_mul_f32 v[32:33], v[0:1], v[32:33] op_sel_hi:[0,1]
	v_pk_mul_f32 v[26:27], v[0:1], v[26:27] op_sel_hi:[0,1]
	v_pk_mul_f32 v[24:25], v[0:1], v[24:25] op_sel_hi:[0,1]
	v_pk_mul_f32 v[22:23], v[0:1], v[22:23] op_sel_hi:[0,1]
	v_pk_mul_f32 v[20:21], v[0:1], v[20:21] op_sel_hi:[0,1]
	v_add_u32_e32 v121, 0x9000, v122
	v_mov_b32_e32 v0, v114
	s_cmp_lg_u64 s[0:1], 0
	v_readlane_b32 s53, v244, 4
	v_readlane_b32 s54, v244, 5
	v_readlane_b32 s55, v244, 6
	v_readlane_b32 s56, v244, 7
	v_readlane_b32 s57, v244, 8
	v_readlane_b32 s58, v244, 9
	v_readlane_b32 s59, v244, 10
	s_mov_b64 s[18:19], 0x1000
	s_mov_b32 s20, 0xf149f2ca
	v_readlane_b32 s21, v244, 16
	v_pk_mul_f32 v[50:51], v[2:3], v[50:51] op_sel_hi:[0,1]
	v_pk_mul_f32 v[48:49], v[2:3], v[48:49] op_sel_hi:[0,1]
	v_pk_mul_f32 v[42:43], v[2:3], v[42:43] op_sel_hi:[0,1]
	v_pk_mul_f32 v[40:41], v[2:3], v[40:41] op_sel_hi:[0,1]
	v_pk_mul_f32 v[30:31], v[2:3], v[30:31] op_sel_hi:[0,1]
	v_pk_mul_f32 v[28:29], v[2:3], v[28:29] op_sel_hi:[0,1]
	s_barrier
	ds_write_b128 v122, v[44:47] offset:36864
	ds_write_b128 v122, v[48:51] offset:40960
	ds_write_b128 v122, v[40:43] offset:45056
	ds_write_b128 v122, v[28:31] offset:49152
	ds_write_b128 v122, v[32:35] offset:53248
	ds_write_b128 v122, v[36:39] offset:57344
	ds_write_b128 v122, v[24:27] offset:61440
	ds_write_b128 v121, v[20:23] offset:28672
	s_cbranch_scc0 .LBB0_387
	v_ashrrev_i32_e32 v2, 6, v0
	v_bfe_u32 v3, v0, 3, 3
	v_bfe_u32 v21, v0, 4, 1
	v_lshlrev_b32_e32 v22, 1, v2
	v_lshl_or_b32 v3, v2, 3, v3
	v_and_b32_e32 v20, 7, v0
	v_and_or_b32 v21, v22, 2, v21
	v_and_b32_e32 v22, 4, v22
	s_movk_i32 s2, 0x880
	v_bitop3_b32 v20, v21, v20, v22 bitop3:0x36
	v_mul_lo_u32 v21, v3, s2
	s_ff1_i32_b64 s4, s[0:1]
	s_add_u32 s2, s0, -1
	v_lshl_or_b32 v96, v20, 3, v21
	v_lshlrev_b32_e32 v20, 12, v3
	v_lshrrev_b32_e32 v3, 1, v3
	s_addc_u32 s3, s1, -1
	s_mul_i32 s5, s4, 0x44000
	v_xor_b32_e32 v3, v3, v0
	s_add_u32 s10, s6, s5
	v_lshlrev_b32_e32 v3, 3, v3
	v_lshlrev_b32_e32 v123, 10, v2
	s_addc_u32 s11, s7, 0
	v_ashrrev_i32_e32 v97, 31, v96
	v_add_u32_e32 v98, 0x11000, v96
	v_and_or_b32 v100, v3, 56, v20
	v_lshl_add_u64 v[2:3], v[96:97], 1, s[10:11]
	s_mov_b64 s[14:15], 0xc00
	v_readfirstlane_b32 s12, v123
	v_lshl_add_u64 v[2:3], v[2:3], 0, s[14:15]
	s_mov_b32 m0, s12
	v_ashrrev_i32_e32 v99, 31, v98
	v_add_u32_e32 v20, 0x1000, v123
	s_lshl_b32 s5, s4, 7
	global_load_lds_dwordx4 v[2:3], off
	v_lshl_add_u64 v[2:3], v[98:99], 1, s[10:11]
	v_readfirstlane_b32 s10, v20
	s_mov_b32 m0, s10
	s_add_u32 s10, s8, s5
	v_add_u32_e32 v20, 0x2000, v123
	v_add_u32_e32 v102, 0x20000, v100
	v_lshl_add_u64 v[2:3], v[2:3], 0, s[14:15]
	s_addc_u32 s11, s9, 0
	v_ashrrev_i32_e32 v101, 31, v100
	v_readfirstlane_b32 s5, v20
	v_add_u32_e32 v20, 0x3000, v123
	global_load_lds_dwordx4 v[2:3], off
	v_lshl_add_u64 v[2:3], v[100:101], 1, s[10:11]
	s_mov_b32 m0, s5
	v_ashrrev_i32_e32 v103, 31, v102
	v_readfirstlane_b32 s5, v20
	global_load_lds_dwordx4 v[2:3], off
	v_lshl_add_u64 v[2:3], v[102:103], 1, s[10:11]
	s_mov_b32 m0, s5
	v_lshrrev_b32_e32 v20, 1, v0
	global_load_lds_dwordx4 v[2:3], off
	v_bfe_u32 v2, v0, 4, 2
	v_and_b32_e32 v3, 15, v0
	v_bfe_u32 v21, v0, 1, 3
	v_lshlrev_b32_e32 v22, 1, v0
	v_and_b32_e32 v0, 3, v0
	v_bitop3_b32 v20, v2, v20, 7 bitop3:0x78
	s_waitcnt vmcnt(0)
	v_lshl_or_b32 v124, v3, 3, v108
	v_and_or_b32 v0, v22, 24, v0
	v_lshlrev_b32_e32 v125, 4, v20
	v_bitop3_b32 v20, v2, v21, 4 bitop3:0x36
	v_lshlrev_b32_e32 v127, 3, v2
	v_lshlrev_b32_e32 v128, 7, v3
	v_mov_b32_e32 v2, v1
	v_mov_b32_e32 v3, v1
	v_lshlrev_b32_e32 v126, 4, v20
	v_lshlrev_b32_e32 v129, 7, v0
	v_mov_b32_e32 v0, v1
	v_mov_b64_e32 v[22:23], v[2:3]
	v_mov_b64_e32 v[26:27], v[2:3]
	v_mov_b64_e32 v[30:31], v[2:3]
	v_mov_b64_e32 v[34:35], v[2:3]
	v_mov_b64_e32 v[38:39], v[2:3]
	v_mov_b64_e32 v[42:43], v[2:3]
	v_mov_b64_e32 v[46:47], v[2:3]
	v_mov_b64_e32 v[50:51], v[2:3]
	s_and_b64 s[2:3], s[2:3], s[0:1]
	s_mov_b32 s10, 0
	v_mov_b32_e32 v130, 0xf149f2ca
	v_mov_b32_e32 v104, 0
	v_mov_b64_e32 v[20:21], v[0:1]
	v_mov_b64_e32 v[24:25], v[0:1]
	v_mov_b64_e32 v[28:29], v[0:1]
	v_mov_b64_e32 v[32:33], v[0:1]
	v_mov_b64_e32 v[36:37], v[0:1]
	v_mov_b64_e32 v[40:41], v[0:1]
	v_mov_b64_e32 v[44:45], v[0:1]
	v_mov_b64_e32 v[48:49], v[0:1]
	v_mov_b32_e32 v105, 0
	v_mov_b32_e32 v0, 0xf149f2ca
	s_mov_b32 s16, 0xefa18f08
	v_lshlrev_b32_e32 v246, 1, v96
	v_lshlrev_b32_e32 v247, 1, v98
	v_lshlrev_b32_e32 v248, 1, v100
	v_lshlrev_b32_e32 v249, 1, v102
	s_waitcnt vmcnt(0) lgkmcnt(0)
	s_barrier
	s_cmp_lg_u64 s[2:3], 0
	s_cbranch_scc1 .LBB0_371
	s_branch .LBB0_370
	.p2alignl 7, 3212836864

; __device__ __forceinline__ f32x4 zero4() { return (f32x4){0.f, 0.f, 0.f, 0.f}; }
; #define NSA_GATE(qt, br) sigmoidf_(glog[qt][br])
; template <int KW, int VD, bool SEL> ...
;     ...
;     if (!tiles) return;
;     int koff[NKI], voff[NVI];
; #pragma unroll
;     for (int i = 0; i < NKI; ++i) {
;         const int row = (w + 4 * i) * KRPI + lane / KCPR, cp = lane % KCPR;
;         const int f = (KW == 64) ? (((row >> 1) & 1) | (((row >> 3) & 1) << 1) | (((row >> 4) & 1) << 2)) : ((row & 3) | (((row >> 3) & 3) << 2));
;         koff[i] = row * ldk + (cp ^ f) * 8;
;     }
; #pragma unroll
;     for (int i = 0; i < NVI; ++i) {
;         const int row = (w + 4 * i) * 8 + (lane >> 3), cp = lane & 7;
;         voff[i] = row * S + (cp ^ ((row >> 1) & 7)) * 8;
;     }
;     ...
;     int j = __ffsll((long long)tiles) - 1; tiles &= tiles - 1;
;     FL_ISSUE(0, j);
;     asm volatile("s_waitcnt vmcnt(0)" ::: "memory");
;     __syncthreads();
;     int cur = 0;
;     const int kswz = (KW == 64) ? ((fr >> 1) & 7) : fr;
;     const int vswz = (fr >> 1) & 7;
;     while (true) {
; __device__ __forceinline__ void nsa_tile(const Params& p, int qb, int bg, char* smem) {
;     ...
; #pragma unroll
;         for (int qt = 0; qt < 2; ++qt) {
;             const float sc = NSA_GATE(qt, 1) / lr[qt];
; #pragma unroll
;             for (int dt = 0; dt < 4; ++dt) ((f32x4*)park)[(qt * 4 + dt) * 256 + tid] = ((f32x4*)park)[(qt * 4 + dt) * 256 + tid] + O[qt][dt] * sc;
;         }
;     }
;     {
;         f32x4 O[2][4];
; #pragma unroll
;         for (int qt = 0; qt < 2; ++qt)
; #pragma unroll
;             for (int dt = 0; dt < 4; ++dt) O[qt][dt] = zero4();
;         float mr[2] = {-1e30f, -1e30f}, lr[2] = {0.f, 0.f};
;         const int lo[2] = {tpos[0] - 512, tpos[1] - 512};
;         const u64 ones[2] = {~0ull, ~0ull};
;         int jlo = t0 - 511; jlo = jlo < 0 ? 0 : (jlo >> 6);
;         const u64 upto = (cur0 == 63) ? ~0ull : ((1ull << (cur0 + 1)) - 1ull);
;         const u64 tiles = upto & ~((1ull << jlo) - 1ull);
;         flash_branch<64, 64, false>(tiles, projA + (size_t)b * S * LDA + 1792 + g * 64, LDA, projVT + ((size_t)b * 512 + 256 + g * 64) * S, 0,
;                                     qf, O, mr, lr, tpos, ones, lo, t0, t0 + 31 - 512, smem);
.LBB0_388:
	v_and_b32_e32 v0, 0xffff0000, v120
	v_mul_f32_e32 v0, 0xbfb8aa3b, v0
	v_exp_f32_e32 v0, v0
	v_lshlrev_b32_e32 v60, 16, v111
	ds_read_b128 v[52:55], v122 offset:36864
	ds_read_b128 v[56:59], v122 offset:40960
	v_readlane_b32 s3, v244, 15
	v_add_f32_e32 v0, 1.0, v0
	v_rcp_f32_e32 v0, v0
	s_lshr_b32 s2, s3, 1
	v_div_scale_f32 v61, s[0:1], v3, v3, v0
	v_rcp_f32_e32 v62, v61
	v_div_scale_f32 v63, vcc, v0, v3, v0
	v_fma_f32 v64, -v61, v62, 1.0
	v_fmac_f32_e32 v62, v64, v62
	v_mul_f32_e32 v64, v63, v62
	v_fma_f32 v65, -v61, v64, v63
	v_fmac_f32_e32 v64, v65, v62
	v_fma_f32 v61, -v61, v64, v63
	v_div_fmas_f32 v61, v61, v62, v64
	v_div_fixup_f32 v0, v61, v3, v0
	v_mul_f32_e32 v3, 0xbfb8aa3b, v60
	v_exp_f32_e32 v3, v3
	s_waitcnt lgkmcnt(1)
	v_pk_fma_f32 v[50:51], v[50:51], v[0:1], v[54:55] op_sel_hi:[1,0,1]
	v_pk_fma_f32 v[48:49], v[48:49], v[0:1], v[52:53] op_sel_hi:[1,0,1]
	ds_write_b128 v122, v[48:51] offset:36864
	ds_read_b128 v[48:51], v122 offset:45056
	v_add_f32_e32 v3, 1.0, v3
	v_rcp_f32_e32 v3, v3
	s_waitcnt lgkmcnt(2)
	v_pk_fma_f32 v[46:47], v[46:47], v[0:1], v[58:59] op_sel_hi:[1,0,1]
	v_pk_fma_f32 v[44:45], v[44:45], v[0:1], v[56:57] op_sel_hi:[1,0,1]
	ds_write_b128 v122, v[44:47] offset:40960
	ds_read_b128 v[44:47], v122 offset:49152
	s_waitcnt lgkmcnt(2)
	v_pk_fma_f32 v[42:43], v[42:43], v[0:1], v[50:51] op_sel_hi:[1,0,1]
	v_pk_fma_f32 v[40:41], v[40:41], v[0:1], v[48:49] op_sel_hi:[1,0,1]
	ds_write_b128 v122, v[40:43] offset:45056
	v_div_scale_f32 v40, s[0:1], v2, v2, v3
	v_rcp_f32_e32 v41, v40
	s_waitcnt lgkmcnt(1)
	v_pk_fma_f32 v[38:39], v[38:39], v[0:1], v[46:47] op_sel_hi:[1,0,1]
	v_pk_fma_f32 v[36:37], v[36:37], v[0:1], v[44:45] op_sel_hi:[1,0,1]
	ds_write_b128 v122, v[36:39] offset:49152
	v_fma_f32 v0, -v40, v41, 1.0
	v_fmac_f32_e32 v41, v0, v41
	v_div_scale_f32 v0, vcc, v3, v2, v3
	v_mul_f32_e32 v42, v0, v41
	v_fma_f32 v36, -v40, v42, v0
	v_fmac_f32_e32 v42, v36, v41
	ds_read_b128 v[36:39], v122 offset:53248
	v_fma_f32 v0, -v40, v42, v0
	s_add_i32 s0, s21, 0xfffffe01
	v_div_fmas_f32 v0, v0, v41, v42
	s_ashr_i32 s0, s0, 6
	v_div_fixup_f32 v0, v0, v2, v3
	s_cmp_gt_u32 s3, 15
	s_waitcnt lgkmcnt(0)
	v_pk_fma_f32 v[34:35], v[34:35], v[0:1], v[38:39] op_sel_hi:[1,0,1]
	v_pk_fma_f32 v[32:33], v[32:33], v[0:1], v[36:37] op_sel_hi:[1,0,1]
	s_cselect_b32 s3, s0, 0
	s_add_i32 s0, s2, 1
	ds_read_b128 v[40:43], v122 offset:57344
	ds_read_b128 v[36:39], v121 offset:28672
	ds_write_b128 v122, v[32:35] offset:53248
	ds_read_b128 v[32:35], v122 offset:61440
	s_lshl_b64 s[0:1], -1, s0
	s_not_b64 s[0:1], s[0:1]
	s_cmp_lg_u32 s2, 63
	s_cselect_b32 s1, s1, -1
	s_cselect_b32 s0, s0, -1
	s_lshl_b64 s[2:3], -1, s3
	s_and_b64 s[0:1], s[2:3], s[0:1]
	s_waitcnt lgkmcnt(3)
	v_pk_fma_f32 v[30:31], v[30:31], v[0:1], v[42:43] op_sel_hi:[1,0,1]
	v_pk_fma_f32 v[28:29], v[28:29], v[0:1], v[40:41] op_sel_hi:[1,0,1]
	s_waitcnt lgkmcnt(0)
	v_pk_fma_f32 v[26:27], v[26:27], v[0:1], v[34:35] op_sel_hi:[1,0,1]
	v_pk_fma_f32 v[24:25], v[24:25], v[0:1], v[32:33] op_sel_hi:[1,0,1]
	v_pk_fma_f32 v[22:23], v[22:23], v[0:1], v[38:39] op_sel_hi:[1,0,1]
	v_pk_fma_f32 v[20:21], v[20:21], v[0:1], v[36:37] op_sel_hi:[1,0,1]
	v_mov_b32_e32 v0, v114
	s_cmp_eq_u64 s[0:1], 0
	ds_write_b128 v122, v[28:31] offset:57344
	ds_write_b128 v122, v[24:27] offset:61440
	ds_write_b128 v121, v[20:23] offset:28672
	s_cbranch_scc1 .LBB0_337
	v_ashrrev_i32_e32 v2, 6, v0
	s_add_u32 s8, s8, 0x200000
	v_bfe_u32 v3, v0, 3, 3
	v_bfe_u32 v21, v0, 4, 1
	v_lshlrev_b32_e32 v22, 1, v2
	s_addc_u32 s9, s9, 0
	s_add_i32 s10, s21, 0xfffffe1f
	v_lshl_or_b32 v3, v2, 3, v3
	v_and_b32_e32 v20, 7, v0
	v_and_or_b32 v21, v22, 2, v21
	v_and_b32_e32 v22, 4, v22
	s_movk_i32 s2, 0x880
	v_bitop3_b32 v20, v21, v20, v22 bitop3:0x36
	v_mul_lo_u32 v21, v3, s2
	s_ff1_i32_b64 s4, s[0:1]
	s_add_u32 s2, s0, -1
	v_lshl_or_b32 v96, v20, 3, v21
	v_lshlrev_b32_e32 v20, 12, v3
	v_lshrrev_b32_e32 v3, 1, v3
	s_addc_u32 s3, s1, -1
	s_mul_i32 s5, s4, 0x44000
	v_xor_b32_e32 v3, v3, v0
	s_add_u32 s12, s6, s5
	v_lshlrev_b32_e32 v3, 3, v3
	v_lshlrev_b32_e32 v106, 10, v2
	s_addc_u32 s13, s7, 0
	v_ashrrev_i32_e32 v97, 31, v96
	v_add_u32_e32 v98, 0x11000, v96
	v_and_or_b32 v100, v3, 56, v20
	v_lshl_add_u64 v[2:3], v[96:97], 1, s[12:13]
	s_mov_b64 s[14:15], 0xe00
	v_readfirstlane_b32 s11, v106
	s_lshl_b32 s5, s4, 7
	v_lshl_add_u64 v[2:3], v[2:3], 0, s[14:15]
	s_mov_b32 m0, s11
	v_ashrrev_i32_e32 v99, 31, v98
	v_add_u32_e32 v20, 0x1000, v106
	global_load_lds_dwordx4 v[2:3], off
	v_lshl_add_u64 v[2:3], v[98:99], 1, s[12:13]
	v_readfirstlane_b32 s11, v20
	s_add_u32 s12, s8, s5
	v_add_u32_e32 v20, 0x2000, v106
	v_add_u32_e32 v102, 0x20000, v100
	v_lshl_add_u64 v[2:3], v[2:3], 0, s[14:15]
	s_mov_b32 m0, s11
	s_addc_u32 s13, s9, 0
	v_ashrrev_i32_e32 v101, 31, v100
	v_readfirstlane_b32 s5, v20
	v_add_u32_e32 v20, 0x3000, v106
	global_load_lds_dwordx4 v[2:3], off
	v_lshl_add_u64 v[2:3], v[100:101], 1, s[12:13]
	s_mov_b32 m0, s5
	v_ashrrev_i32_e32 v103, 31, v102
	v_readfirstlane_b32 s5, v20
	global_load_lds_dwordx4 v[2:3], off
	v_lshl_add_u64 v[2:3], v[102:103], 1, s[12:13]
	s_mov_b32 m0, s5
	v_lshrrev_b32_e32 v20, 1, v0
	global_load_lds_dwordx4 v[2:3], off
	v_bfe_u32 v2, v0, 4, 2
	v_and_b32_e32 v3, 15, v0
	v_bfe_u32 v21, v0, 1, 3
	v_lshlrev_b32_e32 v22, 1, v0
	v_and_b32_e32 v0, 3, v0
	v_bitop3_b32 v20, v2, v20, 7 bitop3:0x78
	s_waitcnt vmcnt(0)
	v_and_or_b32 v0, v22, 24, v0
	v_lshlrev_b32_e32 v123, 4, v20
	v_bitop3_b32 v20, v2, v21, 4 bitop3:0x36
	v_lshlrev_b32_e32 v125, 3, v2
	v_lshlrev_b32_e32 v126, 7, v3
	v_mov_b32_e32 v2, v1
	v_mov_b32_e32 v3, v1
	v_lshlrev_b32_e32 v124, 4, v20
	v_lshlrev_b32_e32 v127, 7, v0
	v_mov_b32_e32 v0, v1
	v_mov_b64_e32 v[22:23], v[2:3]
	v_mov_b64_e32 v[26:27], v[2:3]
	v_mov_b64_e32 v[30:31], v[2:3]
	v_mov_b64_e32 v[34:35], v[2:3]
	v_mov_b64_e32 v[38:39], v[2:3]
	v_mov_b64_e32 v[42:43], v[2:3]
	v_mov_b64_e32 v[46:47], v[2:3]
	v_mov_b64_e32 v[50:51], v[2:3]
	v_add_u32_e32 v107, 0xfffffe00, v94
	v_add_u32_e32 v120, 0xfffffe10, v94
	s_and_b64 s[2:3], s[2:3], s[0:1]
	s_mov_b32 s11, 0
	v_mov_b32_e32 v128, 0xf149f2ca
	v_mov_b32_e32 v104, 0
	v_mov_b64_e32 v[20:21], v[0:1]
	v_mov_b64_e32 v[24:25], v[0:1]
	v_mov_b64_e32 v[28:29], v[0:1]
	v_mov_b64_e32 v[32:33], v[0:1]
	v_mov_b64_e32 v[36:37], v[0:1]
	v_mov_b64_e32 v[40:41], v[0:1]
	v_mov_b64_e32 v[44:45], v[0:1]
	v_mov_b64_e32 v[48:49], v[0:1]
	v_mov_b32_e32 v105, 0
	v_mov_b32_e32 v0, 0xf149f2ca
	v_lshlrev_b32_e32 v250, 1, v96
	v_lshlrev_b32_e32 v251, 1, v98
	v_lshlrev_b32_e32 v252, 1, v100
	v_lshlrev_b32_e32 v253, 1, v102
	s_waitcnt vmcnt(0) lgkmcnt(0)
	s_barrier
	s_cmp_lg_u64 s[2:3], 0
	s_cbranch_scc1 .LBB0_392
	s_branch .LBB0_391
	.p2alignl 7, 3212836864

; template <class Epi>
; __device__ __forceinline__ void gemm_tile(const bf16_t* __restrict__ A, const bf16_t* __restrict__ Bt, int K, int row0, int col0, const Epi& epi, char* smem,
;                                           bool prefetched, bool nvalid, int nrow0, int ncol0) {
;     ...
;     for (int kt = 0; kt < nk; ++kt) {
;         const int cur = kt & 1;
;         if (kt + 1 < nk) GLDS_STAGE(cur ^ 1, pA, pB, kt + 1);
;         const char* cb = smem + cur * 2 * TILE_B;
; #pragma unroll
;         for (int ks = 0; ks < 2; ++ks) {
;             bf16x8 a[4], b[4];
; #pragma unroll
;             for (int m = 0; m < 4; ++m) a[m] = *(const bf16x8*)(cb + offA[m][ks]);
; #pragma unroll
;             for (int n = 0; n < 4; ++n) b[n] = *(const bf16x8*)(cb + offB[n][ks]);
.LBB0_460:
	v_readfirstlane_b32 s98, v94
	v_readfirstlane_b32 s99, v95
	v_readfirstlane_b32 s8, v96
	v_readfirstlane_b32 s100, v102
	v_readfirstlane_b32 s101, v103
	v_readfirstlane_b32 s12, v149
	s_nop 3
	s_sub_u32 s13, s8, s98
	s_and_b32 s98, s98, 0xffffff80
	s_and_b32 s100, s100, 0xffffff80
	s_nop 1
	v_subrev_u32_e32 v254, s98, v94
	v_subrev_u32_e32 v255, s100, v102
	s_add_i32 s11, s12, 0x8000
	s_mov_b32 m0, s11
	s_nop 0
	global_load_lds_dwordx4 v254, s[98:99]
	s_add_i32 m0, s11, 0x1000
	s_add_u32 s8, s98, s13
	s_addc_u32 s9, s99, 0
	global_load_lds_dwordx4 v254, s[8:9]
	s_add_i32 m0, s11, 0x2000
	s_add_u32 s8, s8, s13
	s_addc_u32 s9, s9, 0
	global_load_lds_dwordx4 v254, s[8:9]
	s_add_i32 m0, s11, 0x3000
	s_add_u32 s8, s8, s13
	s_addc_u32 s9, s9, 0
	global_load_lds_dwordx4 v254, s[8:9]
	s_add_u32 s98, s98, 0x80
	s_addc_u32 s99, s99, 0
	ds_read_b128 v[174:177], v110
	ds_read_b128 v[94:97], v87 offset:16384
	ds_read_b128 v[98:101], v87 offset:16896
	ds_read_b128 v[102:105], v87 offset:20480
	ds_read_b128 v[106:109], v87 offset:20992
	ds_read_b128 v[178:181], v110 offset:2048
	ds_read_b128 v[246:249], v110 offset:4096
	ds_read_b128 v[250:253], v110 offset:6144
	s_setprio 1
	.p2alignl 7, 3212836864

; template <class Epi>
; __device__ __forceinline__ void gemm_tile(const bf16_t* __restrict__ A, const bf16_t* __restrict__ Bt, int K, int row0, int col0, const Epi& epi, char* smem,
;                                           bool prefetched, bool nvalid, int nrow0, int ncol0) {
;     ...
;     for (int kt = 0; kt < nk; ++kt) {
;         const int cur = kt & 1;
;         if (kt + 1 < nk) GLDS_STAGE(cur ^ 1, pA, pB, kt + 1);
;         const char* cb = smem + cur * 2 * TILE_B;
; #pragma unroll
;         for (int ks = 0; ks < 2; ++ks) {
;             bf16x8 a[4], b[4];
; #pragma unroll
;             for (int m = 0; m < 4; ++m) a[m] = *(const bf16x8*)(cb + offA[m][ks]);
; #pragma unroll
;             for (int n = 0; n < 4; ++n) b[n] = *(const bf16x8*)(cb + offB[n][ks]);
.LBB0_563:
	v_readfirstlane_b32 s98, v110
	v_readfirstlane_b32 s99, v111
	v_readfirstlane_b32 s10, v118
	v_readfirstlane_b32 s100, v124
	v_readfirstlane_b32 s101, v125
	v_readfirstlane_b32 s17, v149
	s_nop 3
	s_sub_u32 s18, s10, s98
	s_and_b32 s98, s98, 0xffffff80
	s_and_b32 s100, s100, 0xffffff80
	s_nop 1
	v_subrev_u32_e32 v254, s98, v110
	v_subrev_u32_e32 v255, s100, v124
	s_add_i32 s13, s17, 0x8000
	s_mov_b32 m0, s13
	s_nop 0
	global_load_lds_dwordx4 v254, s[98:99]
	s_add_i32 m0, s13, 0x1000
	s_add_u32 s10, s98, s18
	s_addc_u32 s11, s99, 0
	global_load_lds_dwordx4 v254, s[10:11]
	s_add_i32 m0, s13, 0x2000
	s_add_u32 s10, s10, s18
	s_addc_u32 s11, s11, 0
	global_load_lds_dwordx4 v254, s[10:11]
	s_add_i32 m0, s13, 0x3000
	s_add_u32 s10, s10, s18
	s_addc_u32 s11, s11, 0
	global_load_lds_dwordx4 v254, s[10:11]
	s_add_u32 s98, s98, 0x80
	s_addc_u32 s99, s99, 0
	ds_read_b128 v[192:195], v85
	ds_read_b128 v[118:121], v142 offset:16384
	ds_read_b128 v[122:125], v142 offset:16896
	ds_read_b128 v[126:129], v142 offset:20480
	ds_read_b128 v[172:175], v142 offset:20992
	ds_read_b128 v[196:199], v85 offset:2048
	ds_read_b128 v[246:249], v85 offset:4096
	ds_read_b128 v[250:253], v85 offset:6144
	s_setprio 1
	.p2alignl 7, 3212836864

; template <class Epi>
; __device__ __forceinline__ void gemm_tile(const bf16_t* __restrict__ A, const bf16_t* __restrict__ Bt, int K, int row0, int col0, const Epi& epi, char* smem,
;                                           bool prefetched, bool nvalid, int nrow0, int ncol0) {
;     ...
;     for (int kt = 0; kt < nk; ++kt) {
;         const int cur = kt & 1;
;         if (kt + 1 < nk) GLDS_STAGE(cur ^ 1, pA, pB, kt + 1);
;         const char* cb = smem + cur * 2 * TILE_B;
; #pragma unroll
;         for (int ks = 0; ks < 2; ++ks) {
;             bf16x8 a[4], b[4];
; #pragma unroll
;             for (int m = 0; m < 4; ++m) a[m] = *(const bf16x8*)(cb + offA[m][ks]);
; #pragma unroll
;             for (int n = 0; n < 4; ++n) b[n] = *(const bf16x8*)(cb + offB[n][ks]);
.LBB0_619:
	v_readfirstlane_b32 s98, v92
	v_readfirstlane_b32 s99, v93
	v_readfirstlane_b32 s8, v94
	v_readfirstlane_b32 s100, v100
	v_readfirstlane_b32 s101, v101
	v_readfirstlane_b32 s12, v149
	s_nop 3
	s_sub_u32 s13, s8, s98
	s_and_b32 s98, s98, 0xffffff80
	s_and_b32 s100, s100, 0xffffff80
	s_nop 1
	v_subrev_u32_e32 v254, s98, v92
	v_subrev_u32_e32 v255, s100, v100
	s_add_i32 s11, s12, 0x8000
	s_mov_b32 m0, s11
	s_nop 0
	global_load_lds_dwordx4 v254, s[98:99]
	s_add_i32 m0, s11, 0x1000
	s_add_u32 s8, s98, s13
	s_addc_u32 s9, s99, 0
	global_load_lds_dwordx4 v254, s[8:9]
	s_add_i32 m0, s11, 0x2000
	s_add_u32 s8, s8, s13
	s_addc_u32 s9, s9, 0
	global_load_lds_dwordx4 v254, s[8:9]
	s_add_i32 m0, s11, 0x3000
	s_add_u32 s8, s8, s13
	s_addc_u32 s9, s9, 0
	global_load_lds_dwordx4 v254, s[8:9]
	s_add_u32 s98, s98, 0x80
	s_addc_u32 s99, s99, 0
	ds_read_b128 v[174:177], v108
	ds_read_b128 v[92:95], v110 offset:16384
	ds_read_b128 v[96:99], v110 offset:16896
	ds_read_b128 v[100:103], v110 offset:20480
	ds_read_b128 v[104:107], v110 offset:20992
	ds_read_b128 v[178:181], v108 offset:2048
	ds_read_b128 v[246:249], v108 offset:4096
	ds_read_b128 v[250:253], v108 offset:6144
	s_setprio 1
	.p2alignl 7, 3212836864

; template <class Epi>
; __device__ __forceinline__ void gemm_tile(const bf16_t* __restrict__ A, const bf16_t* __restrict__ Bt, int K, int row0, int col0, const Epi& epi, char* smem,
;                                           bool prefetched, bool nvalid, int nrow0, int ncol0) {
;     ...
;     for (int kt = 0; kt < nk; ++kt) {
;         const int cur = kt & 1;
;         if (kt + 1 < nk) GLDS_STAGE(cur ^ 1, pA, pB, kt + 1);
;         const char* cb = smem + cur * 2 * TILE_B;
; #pragma unroll
;         for (int ks = 0; ks < 2; ++ks) {
;             bf16x8 a[4], b[4];
; #pragma unroll
;             for (int m = 0; m < 4; ++m) a[m] = *(const bf16x8*)(cb + offA[m][ks]);
; #pragma unroll
;             for (int n = 0; n < 4; ++n) b[n] = *(const bf16x8*)(cb + offB[n][ks]);
.LBB0_723:
	v_readfirstlane_b32 s98, v64
	v_readfirstlane_b32 s99, v65
	v_readfirstlane_b32 s12, v66
	v_readfirstlane_b32 s100, v72
	v_readfirstlane_b32 s101, v73
	v_readfirstlane_b32 s15, v149
	s_nop 3
	s_sub_u32 s16, s12, s98
	s_and_b32 s98, s98, 0xffffff80
	s_and_b32 s100, s100, 0xffffff80
	s_nop 1
	v_subrev_u32_e32 v254, s98, v64
	v_subrev_u32_e32 v255, s100, v72
	s_add_i32 s14, s15, 0x8000
	s_mov_b32 m0, s14
	s_nop 0
	global_load_lds_dwordx4 v254, s[98:99]
	s_add_i32 m0, s14, 0x1000
	s_add_u32 s12, s98, s16
	s_addc_u32 s13, s99, 0
	global_load_lds_dwordx4 v254, s[12:13]
	s_add_i32 m0, s14, 0x2000
	s_add_u32 s12, s12, s16
	s_addc_u32 s13, s13, 0
	global_load_lds_dwordx4 v254, s[12:13]
	s_add_i32 m0, s14, 0x3000
	s_add_u32 s12, s12, s16
	s_addc_u32 s13, s13, 0
	global_load_lds_dwordx4 v254, s[12:13]
	s_add_u32 s98, s98, 0x80
	s_addc_u32 s99, s99, 0
	ds_read_b128 v[188:191], v137
	ds_read_b128 v[64:67], v143 offset:16384
	ds_read_b128 v[68:71], v143 offset:16896
	ds_read_b128 v[72:75], v143 offset:20480
	ds_read_b128 v[76:79], v143 offset:20992
	ds_read_b128 v[192:195], v137 offset:2048
	ds_read_b128 v[246:249], v137 offset:4096
	ds_read_b128 v[250:253], v137 offset:6144
	s_setprio 1
	.p2alignl 7, 3212836864

; template <class Epi>
; __device__ __forceinline__ void gemm_tile(const bf16_t* __restrict__ A, const bf16_t* __restrict__ Bt, int K, int row0, int col0, const Epi& epi, char* smem,
;                                           bool prefetched, bool nvalid, int nrow0, int ncol0) {
;     ...
;     for (int kt = 0; kt < nk; ++kt) {
;         const int cur = kt & 1;
;         if (kt + 1 < nk) GLDS_STAGE(cur ^ 1, pA, pB, kt + 1);
;         const char* cb = smem + cur * 2 * TILE_B;
; #pragma unroll
;         for (int ks = 0; ks < 2; ++ks) {
;             bf16x8 a[4], b[4];
; #pragma unroll
;             for (int m = 0; m < 4; ++m) a[m] = *(const bf16x8*)(cb + offA[m][ks]);
; #pragma unroll
;             for (int n = 0; n < 4; ++n) b[n] = *(const bf16x8*)(cb + offB[n][ks]);
.LBB0_766:
	v_readfirstlane_b32 s98, v106
	v_readfirstlane_b32 s99, v107
	v_readfirstlane_b32 s10, v108
	v_readfirstlane_b32 s100, v120
	v_readfirstlane_b32 s101, v121
	v_readfirstlane_b32 s13, v149
	s_nop 3
	s_sub_u32 s16, s10, s98
	s_and_b32 s98, s98, 0xffffff80
	s_and_b32 s100, s100, 0xffffff80
	s_nop 1
	v_subrev_u32_e32 v254, s98, v106
	v_subrev_u32_e32 v255, s100, v120
	s_add_i32 s12, s13, 0x8000
	s_mov_b32 m0, s12
	s_nop 0
	global_load_lds_dwordx4 v254, s[98:99]
	s_add_i32 m0, s12, 0x1000
	s_add_u32 s10, s98, s16
	s_addc_u32 s11, s99, 0
	global_load_lds_dwordx4 v254, s[10:11]
	s_add_i32 m0, s12, 0x2000
	s_add_u32 s10, s10, s16
	s_addc_u32 s11, s11, 0
	global_load_lds_dwordx4 v254, s[10:11]
	s_add_i32 m0, s12, 0x3000
	s_add_u32 s10, s10, s16
	s_addc_u32 s11, s11, 0
	global_load_lds_dwordx4 v254, s[10:11]
	s_add_u32 s98, s98, 0x80
	s_addc_u32 s99, s99, 0
	ds_read_b128 v[190:193], v128
	ds_read_b128 v[106:109], v131 offset:16384
	ds_read_b128 v[118:121], v131 offset:16896
	ds_read_b128 v[122:125], v131 offset:20480
	ds_read_b128 v[170:173], v131 offset:20992
	ds_read_b128 v[194:197], v128 offset:2048
	ds_read_b128 v[198:201], v128 offset:4096
	ds_read_b128 v[246:249], v128 offset:6144
	s_setprio 1
	.p2alignl 7, 3212836864

; __device__ __forceinline__ f32x4 zero4() { return (f32x4){0.f, 0.f, 0.f, 0.f}; }
; __device__ __forceinline__ void diff_tile(const Params& p, int qb, int bh, float lam, char* smem) {
;     int tid = threadIdx.x; asm volatile("" : "+v"(tid));
;     const int lane = tid & 63, w = tid >> 6, fr = lane & 15, fq = lane >> 4;
;     const int b = bh >> 3, h = bh & 7, map = w >> 1, half = w & 1, tw0 = qb * 64 + half * 32;
;     const bf16_t* projA = (const bf16_t*)(p.ws + OFF_PROJA);
;     const bf16_t* projVT = (const bf16_t*)(p.ws + OFF_PROJVT);
;     bf16x8 qf[2][2];
;     int tpos[2];
; #pragma unroll
;     for (int qt = 0; qt < 2; ++qt) {
;         tpos[qt] = tw0 + qt * 16 + fr;
;         const bf16_t* qrow = projA + (size_t)(b * S + tpos[qt]) * LDA + (h * 2 + map) * 64;
; #pragma unroll
;         for (int ks = 0; ks < 2; ++ks) qf[qt][ks] = *(const bf16x8*)(qrow + ks * 32 + fq * 8);
;     }
;     f32x4 O[2][8];
; #pragma unroll
;     for (int qt = 0; qt < 2; ++qt)
; #pragma unroll
;         for (int dt = 0; dt < 8; ++dt) O[qt][dt] = zero4();
;     float mr[2] = {-1e30f, -1e30f}, lr[2] = {0.f, 0.f};
;     const int lo[2] = {-1, -1};
;     const u64 ones[2] = {~0ull, ~0ull};
;     const u64 tiles = (qb == 63) ? ~0ull : ((1ull << (qb + 1)) - 1ull);
;     flash_branch<128, 128, false>(tiles, projA + (size_t)b * S * LDA + 1024 + h * 128, LDA, projVT + ((size_t)b * 1024 + h * 128) * S, map * 64,
;                                   qf, O, mr, lr, tpos, ones, lo, qb * 64, -1, smem);
; __global__ void __launch_bounds__(256, 2) fwd_megakernel(Params p) {
;     ...
;         for (int r = 0; r * G < 4096; ++r) {
;             const int k = (r & 1) ? (G - 1 - (int)blockIdx.x) : (int)blockIdx.x, i = r * G + k;
;             if (i < 4096) diff_tile(p, 63 - (i >> 6), i & 63, lam, smem);
.LBB0_817:
	s_setprio 3
	s_bitcmp0_b32 s17, 0
	v_readlane_b32 s7, v245, 0
	v_readlane_b32 s8, v245, 62
	s_cselect_b32 s7, s7, s8
	s_add_i32 s6, s7, s6
	s_cmpk_gt_i32 s6, 0xfff
	s_cbranch_scc1 .LBB0_816
	v_mov_b32_e32 v172, v114
	s_lshl_b32 s9, s6, 7
	s_and_b32 s18, s9, 0x380
	v_and_b32_e32 v0, 15, v172
	v_ashrrev_i32_e32 v173, 7, v172
	v_lshrrev_b32_e32 v1, 1, v172
	s_and_b32 s7, s6, 0xffffffc0
	v_and_or_b32 v171, v1, 32, v0
	v_lshl_add_u32 v0, v173, 6, s18
	v_readlane_b32 s20, v245, 55
	v_bfe_u32 v170, v172, 4, 2
	s_sub_i32 s19, 0xfc0, s7
	v_ashrrev_i32_e32 v1, 31, v0
	v_readlane_b32 s21, v245, 56
	s_bfe_u32 s8, s6, 0x30003
	v_or_b32_e32 v127, s19, v171
	v_lshl_add_u64 v[0:1], v[0:1], 1, s[20:21]
	v_lshlrev_b32_e32 v124, 4, v170
	v_mov_b32_e32 v125, v119
	s_lshl_b32 s7, s8, 12
	v_lshl_add_u64 v[0:1], v[0:1], 0, v[124:125]
	v_or_b32_e32 v125, 16, v127
	v_add_u32_e32 v118, s7, v127
	v_add_u32_e32 v126, s7, v125
	v_mad_u64_u32 v[2:3], s[10:11], v118, s3, v[0:1]
	v_mad_u64_u32 v[0:1], s[10:11], v126, s3, v[0:1]
	global_load_dwordx4 v[64:67], v[2:3], off
	global_load_dwordx4 v[68:71], v[2:3], off offset:64
	global_load_dwordx4 v[72:75], v[0:1], off
	global_load_dwordx4 v[76:79], v[0:1], off offset:64
	s_ashr_i32 s7, s6, 6
	s_sub_i32 s7, 64, s7
	s_lshl_b64 s[10:11], -1, s7
	s_not_b64 s[10:11], s[10:11]
	s_cmp_gt_u32 s6, 63
	s_cselect_b32 s7, s11, -1
	s_cselect_b32 s6, s10, -1
	v_mov_b32_e32 v0, v114
	s_cmp_eq_u64 s[6:7], 0
	s_cbranch_scc1 .LBB0_838
; template <int KW, int VD, bool SEL> ...
;     constexpr int KROWB = KW * 2, KB = 64 * KROWB, VB = VD * 128, BUFB = KB + VB;
;     constexpr int NKI = KB / 4096, NVI = VB / 4096, KRPI = 1024 / KROWB, KCPR = KROWB / 16;
;     int tid = threadIdx.x; asm volatile("" : "+v"(tid));
;     const int lane = tid & 63, w = tid >> 6, fr = lane & 15, fq = lane >> 4;
;     if (!tiles) return;
;     int koff[NKI], voff[NVI];
; #pragma unroll
;     for (int i = 0; i < NKI; ++i) {
;         const int row = (w + 4 * i) * KRPI + lane / KCPR, cp = lane % KCPR;
;         const int f = (KW == 64) ? (((row >> 1) & 1) | (((row >> 3) & 1) << 1) | (((row >> 4) & 1) << 2)) : ((row & 3) | (((row >> 3) & 3) << 2));
;         koff[i] = row * ldk + (cp ^ f) * 8;
;     }
; #pragma unroll
;     for (int i = 0; i < NVI; ++i) {
;         const int row = (w + 4 * i) * 8 + (lane >> 3), cp = lane & 7;
;         voff[i] = row * S + (cp ^ ((row >> 1) & 7)) * 8;
;     }
;     ...
;     int j = __ffsll((long long)tiles) - 1; tiles &= tiles - 1;
;     FL_ISSUE(0, j);
;     asm volatile("s_waitcnt vmcnt(0)" ::: "memory");
;     __syncthreads();
;     int cur = 0;
;     const int kswz = (KW == 64) ? ((fr >> 1) & 7) : fr;
;     const int vswz = (fr >> 1) & 7;
;     while (true) {
	v_ashrrev_i32_e32 v2, 6, v0
	v_bfe_u32 v1, v0, 4, 2
	v_lshlrev_b32_e32 v3, 2, v2
	v_lshlrev_b32_e32 v6, 1, v2
	v_and_b32_e32 v4, 15, v0
	v_or_b32_e32 v5, v3, v1
	v_and_b32_e32 v6, 12, v6
	s_mul_i32 s9, s8, 0x1100000
	v_mul_lo_u32 v5, v5, s12
	v_bitop3_b32 v6, v6, v4, v1 bitop3:0x36
	s_add_u32 s9, s20, s9
	v_lshl_or_b32 v128, v6, 3, v5
	v_add_u32_e32 v5, 16, v3
	s_addc_u32 s10, s21, 0
	s_lshl_b32 s11, s18, 1
	v_or_b32_e32 v6, v5, v1
	v_lshrrev_b32_e32 v5, 1, v5
	s_add_u32 s20, s9, s11
	v_and_b32_e32 v5, 12, v5
	s_addc_u32 s21, s10, 0
	s_lshl_b32 s8, s8, 23
	v_readlane_b32 s9, v245, 57
	v_mul_lo_u32 v6, v6, s12
	v_bitop3_b32 v5, v5, v4, v1 bitop3:0x36
	v_add_u32_e32 v3, 48, v3
	s_add_u32 s8, s9, s8
	v_readlane_b32 s9, v245, 58
	v_lshl_or_b32 v130, v5, 3, v6
	v_or_b32_e32 v5, v3, v1
	v_lshrrev_b32_e32 v3, 1, v3
	s_addc_u32 s9, s9, 0
	s_lshl_b32 s10, s18, 13
	v_and_b32_e32 v3, 12, v3
	s_add_u32 s22, s8, s10
	v_mul_lo_u32 v5, v5, s12
	v_bitop3_b32 v3, v3, v4, v1 bitop3:0x36
	s_addc_u32 s23, s9, 0
	v_lshl_or_b32 v134, v3, 3, v5
	v_bfe_u32 v3, v0, 3, 3
	v_lshl_or_b32 v3, v2, 3, v3
	s_ff1_i32_b64 s10, s[6:7]
	s_add_u32 s8, s6, -1
	v_lshlrev_b32_e32 v5, 12, v3
	v_lshrrev_b32_e32 v3, 1, v3
	s_addc_u32 s9, s7, -1
	s_mul_i32 s11, s10, 0x44000
	v_xor_b32_e32 v3, v3, v0
	s_add_u32 s24, s20, s11
	v_lshlrev_b32_e32 v3, 3, v3
	v_lshlrev_b32_e32 v174, 10, v2
	s_addc_u32 s25, s21, 0
	v_ashrrev_i32_e32 v129, 31, v128
	v_and_or_b32 v136, v3, 56, v5
	v_lshl_add_u64 v[2:3], v[128:129], 1, s[24:25]
	v_readfirstlane_b32 s26, v174
	v_lshl_add_u64 v[2:3], v[2:3], 0, s[0:1]
	s_mov_b32 m0, s26
	v_ashrrev_i32_e32 v131, 31, v130
	v_add_u32_e32 v5, 0x1000, v174
	v_add_u32_e32 v132, 0x11000, v128
	global_load_lds_dwordx4 v[2:3], off
	v_lshl_add_u64 v[2:3], v[130:131], 1, s[24:25]
	v_readfirstlane_b32 s26, v5
	v_lshl_add_u64 v[2:3], v[2:3], 0, s[0:1]
	s_mov_b32 m0, s26
	v_ashrrev_i32_e32 v133, 31, v132
	v_add_u32_e32 v5, 0x2000, v174
	global_load_lds_dwordx4 v[2:3], off
	v_lshl_add_u64 v[2:3], v[132:133], 1, s[24:25]
	v_readfirstlane_b32 s26, v5
	v_lshl_add_u64 v[2:3], v[2:3], 0, s[0:1]
	s_mov_b32 m0, s26
	v_ashrrev_i32_e32 v135, 31, v134
	v_add_u32_e32 v5, 0x3000, v174
	s_lshl_b32 s11, s10, 7
	global_load_lds_dwordx4 v[2:3], off
	v_lshl_add_u64 v[2:3], v[134:135], 1, s[24:25]
	v_readfirstlane_b32 s24, v5
	s_mov_b32 m0, s24
	s_add_u32 s24, s22, s11
	v_add_u32_e32 v5, 0x4000, v174
	v_add_u32_e32 v138, 0x20000, v136
	v_lshl_add_u64 v[2:3], v[2:3], 0, s[0:1]
	s_addc_u32 s25, s23, 0
	v_ashrrev_i32_e32 v137, 31, v136
	v_readfirstlane_b32 s11, v5
	v_add_u32_e32 v5, 0x5000, v174
	v_add_u32_e32 v140, 0x40000, v136
	global_load_lds_dwordx4 v[2:3], off
	v_lshl_add_u64 v[2:3], v[136:137], 1, s[24:25]
	s_mov_b32 m0, s11
	v_ashrrev_i32_e32 v139, 31, v138
	v_readfirstlane_b32 s11, v5
	v_add_u32_e32 v5, 0x6000, v174
	v_add_u32_e32 v142, 0x60000, v136
	global_load_lds_dwordx4 v[2:3], off
	v_lshl_add_u64 v[2:3], v[138:139], 1, s[24:25]
	s_mov_b32 m0, s11
	v_ashrrev_i32_e32 v141, 31, v140
	v_readfirstlane_b32 s11, v5
	v_add_u32_e32 v5, 0x7000, v174
	global_load_lds_dwordx4 v[2:3], off
	v_lshl_add_u64 v[2:3], v[140:141], 1, s[24:25]
	s_mov_b32 m0, s11
	v_ashrrev_i32_e32 v143, 31, v142
	v_readfirstlane_b32 s11, v5
	global_load_lds_dwordx4 v[2:3], off
	v_lshl_add_u64 v[2:3], v[142:143], 1, s[24:25]
	s_mov_b32 m0, s11
	v_lshlrev_b32_e32 v5, 1, v0
	global_load_lds_dwordx4 v[2:3], off
	v_lshrrev_b32_e32 v2, 1, v0
	v_bfe_u32 v3, v0, 1, 3
	v_and_b32_e32 v0, 3, v0
	v_and_or_b32 v0, v5, 24, v0
	v_lshlrev_b32_e32 v5, 3, v173
	v_or_b32_e32 v6, v1, v5
	v_bitop3_b32 v5, v1, v4, v5 bitop3:0x36
	v_lshlrev_b32_e32 v179, 8, v0
	v_bitop3_b32 v0, v1, v2, 7 bitop3:0x78
	s_waitcnt vmcnt(0)
	v_lshlrev_b32_e32 v175, 4, v5
	v_bitop3_b32 v5, v6, v4, 4 bitop3:0x36
	v_lshlrev_b32_e32 v180, 4, v0
	v_bitop3_b32 v0, v1, v3, 4 bitop3:0x36
	v_mov_b32_e32 v8, v119
	v_mov_b32_e32 v9, v119
	v_mov_b32_e32 v10, v119
	v_mov_b32_e32 v11, v119
	v_lshlrev_b32_e32 v176, 4, v5
	v_lshlrev_b32_e32 v177, 3, v1
	v_lshlrev_b32_e32 v178, 7, v4
	v_lshlrev_b32_e32 v181, 4, v0
	v_mov_b64_e32 v[14:15], v[10:11]
	v_mov_b64_e32 v[18:19], v[10:11]
	v_mov_b64_e32 v[22:23], v[10:11]
	v_mov_b64_e32 v[26:27], v[10:11]
	v_mov_b64_e32 v[30:31], v[10:11]
	v_mov_b64_e32 v[34:35], v[10:11]
	v_mov_b64_e32 v[38:39], v[10:11]
	v_mov_b64_e32 v[42:43], v[10:11]
	v_mov_b64_e32 v[46:47], v[10:11]
	v_mov_b64_e32 v[50:51], v[10:11]
	v_mov_b64_e32 v[54:55], v[10:11]
	v_mov_b64_e32 v[58:59], v[10:11]
	v_mov_b64_e32 v[62:63], v[10:11]
	v_mov_b64_e32 v[4:5], v[8:9]
	v_mov_b64_e32 v[0:1], v[8:9]
	s_and_b64 s[6:7], s[8:9], s[6:7]
	s_mov_b32 s24, 0
	v_mov_b32_e32 v182, 0xf149f2ca
	v_mov_b32_e32 v144, 0
	v_mov_b64_e32 v[12:13], v[8:9]
	v_mov_b64_e32 v[16:17], v[8:9]
	v_mov_b64_e32 v[20:21], v[8:9]
	v_mov_b64_e32 v[24:25], v[8:9]
	v_mov_b64_e32 v[28:29], v[8:9]
	v_mov_b64_e32 v[32:33], v[8:9]
	v_mov_b64_e32 v[36:37], v[8:9]
	v_mov_b64_e32 v[40:41], v[8:9]
	v_mov_b64_e32 v[44:45], v[8:9]
	v_mov_b64_e32 v[48:49], v[8:9]
	v_mov_b64_e32 v[52:53], v[8:9]
	v_mov_b64_e32 v[56:57], v[8:9]
	v_mov_b64_e32 v[60:61], v[8:9]
	v_mov_b64_e32 v[6:7], v[10:11]
	v_mov_b64_e32 v[2:3], v[10:11]
	v_mov_b32_e32 v145, 0
	v_mov_b32_e32 v183, 0xf149f2ca
	v_lshlrev_b32_e32 v246, 1, v128
	v_lshlrev_b32_e32 v247, 1, v130
	v_lshlrev_b32_e32 v248, 1, v132
	v_lshlrev_b32_e32 v249, 1, v134
	v_lshlrev_b32_e32 v250, 1, v136
	v_lshlrev_b32_e32 v251, 1, v138
	v_lshlrev_b32_e32 v252, 1, v140
	v_lshlrev_b32_e32 v253, 1, v142
	s_waitcnt vmcnt(0) lgkmcnt(0)
	s_barrier
	s_cmp_lg_u64 s[6:7], 0
	s_cbranch_scc1 .LBB0_822
	s_branch .LBB0_821
	.p2alignl 7, 3212836864

; template <class Epi>
; __device__ __forceinline__ void gemm_tile(const bf16_t* __restrict__ A, const bf16_t* __restrict__ Bt, int K, int row0, int col0, const Epi& epi, char* smem,
;                                           bool prefetched, bool nvalid, int nrow0, int ncol0) {
;     ...
;     for (int kt = 0; kt < nk; ++kt) {
;         const int cur = kt & 1;
;         if (kt + 1 < nk) GLDS_STAGE(cur ^ 1, pA, pB, kt + 1);
;         const char* cb = smem + cur * 2 * TILE_B;
; #pragma unroll
;         for (int ks = 0; ks < 2; ++ks) {
;             bf16x8 a[4], b[4];
; #pragma unroll
;             for (int m = 0; m < 4; ++m) a[m] = *(const bf16x8*)(cb + offA[m][ks]);
; #pragma unroll
;             for (int n = 0; n < 4; ++n) b[n] = *(const bf16x8*)(cb + offB[n][ks]);
.LBB0_998:
	v_readfirstlane_b32 s98, v106
	v_readfirstlane_b32 s99, v107
	v_readfirstlane_b32 s10, v108
	v_readfirstlane_b32 s100, v120
	v_readfirstlane_b32 s101, v121
	v_readfirstlane_b32 s17, v149
	s_nop 3
	s_sub_u32 s18, s10, s98
	s_and_b32 s98, s98, 0xffffff80
	s_and_b32 s100, s100, 0xffffff80
	s_nop 1
	v_subrev_u32_e32 v254, s98, v106
	v_subrev_u32_e32 v255, s100, v120
	s_add_i32 s13, s17, 0x8000
	s_mov_b32 m0, s13
	s_nop 0
	global_load_lds_dwordx4 v254, s[98:99]
	s_add_i32 m0, s13, 0x1000
	s_add_u32 s10, s98, s18
	s_addc_u32 s11, s99, 0
	global_load_lds_dwordx4 v254, s[10:11]
	s_add_i32 m0, s13, 0x2000
	s_add_u32 s10, s10, s18
	s_addc_u32 s11, s11, 0
	global_load_lds_dwordx4 v254, s[10:11]
	s_add_i32 m0, s13, 0x3000
	s_add_u32 s10, s10, s18
	s_addc_u32 s11, s11, 0
	global_load_lds_dwordx4 v254, s[10:11]
	s_add_u32 s98, s98, 0x80
	s_addc_u32 s99, s99, 0
	ds_read_b128 v[184:187], v130
	ds_read_b128 v[106:109], v133 offset:16384
	ds_read_b128 v[118:121], v133 offset:16896
	ds_read_b128 v[122:125], v133 offset:20480
	ds_read_b128 v[158:161], v133 offset:20992
	ds_read_b128 v[188:191], v130 offset:2048
	ds_read_b128 v[246:249], v130 offset:4096
	ds_read_b128 v[250:253], v130 offset:6144
	s_setprio 1
	.p2alignl 7, 3212836864

; template <class Epi>
; __device__ __forceinline__ void gemm_tile(const bf16_t* __restrict__ A, const bf16_t* __restrict__ Bt, int K, int row0, int col0, const Epi& epi, char* smem,
;                                           bool prefetched, bool nvalid, int nrow0, int ncol0) {
;     ...
;     for (int kt = 0; kt < nk; ++kt) {
;         const int cur = kt & 1;
;         if (kt + 1 < nk) GLDS_STAGE(cur ^ 1, pA, pB, kt + 1);
;         const char* cb = smem + cur * 2 * TILE_B;
; #pragma unroll
;         for (int ks = 0; ks < 2; ++ks) {
;             bf16x8 a[4], b[4];
; #pragma unroll
;             for (int m = 0; m < 4; ++m) a[m] = *(const bf16x8*)(cb + offA[m][ks]);
; #pragma unroll
;             for (int n = 0; n < 4; ++n) b[n] = *(const bf16x8*)(cb + offB[n][ks]);
.LBB0_1054:
	v_readfirstlane_b32 s98, v92
	v_readfirstlane_b32 s99, v93
	v_readfirstlane_b32 s6, v94
	v_readfirstlane_b32 s100, v100
	v_readfirstlane_b32 s101, v101
	v_readfirstlane_b32 s10, v149
	s_nop 3
	s_sub_u32 s11, s6, s98
	s_and_b32 s98, s98, 0xffffff80
	s_and_b32 s100, s100, 0xffffff80
	s_nop 1
	v_subrev_u32_e32 v254, s98, v92
	v_subrev_u32_e32 v255, s100, v100
	s_add_i32 s9, s10, 0x8000
	s_mov_b32 m0, s9
	s_nop 0
	global_load_lds_dwordx4 v254, s[98:99]
	s_add_i32 m0, s9, 0x1000
	s_add_u32 s6, s98, s11
	s_addc_u32 s7, s99, 0
	global_load_lds_dwordx4 v254, s[6:7]
	s_add_i32 m0, s9, 0x2000
	s_add_u32 s6, s6, s11
	s_addc_u32 s7, s7, 0
	global_load_lds_dwordx4 v254, s[6:7]
	s_add_i32 m0, s9, 0x3000
	s_add_u32 s6, s6, s11
	s_addc_u32 s7, s7, 0
	global_load_lds_dwordx4 v254, s[6:7]
	s_add_u32 s98, s98, 0x80
	s_addc_u32 s99, s99, 0
	ds_read_b128 v[150:153], v108
	ds_read_b128 v[92:95], v110 offset:16384
	ds_read_b128 v[96:99], v110 offset:16896
	ds_read_b128 v[100:103], v110 offset:20480
	ds_read_b128 v[104:107], v110 offset:20992
	ds_read_b128 v[154:157], v108 offset:2048
	ds_read_b128 v[246:249], v108 offset:4096
	ds_read_b128 v[250:253], v108 offset:6144
	s_setprio 1
	.p2alignl 7, 3212836864

; __global__ void __launch_bounds__(256, 2) fwd_megakernel(Params p) {
;     ...
;     rmsnorm_phase(p.out, p.in[20], nullptr, p.out);
; }
	.text
	.p2alignl 7, 3212836864
	.fill 256, 4, 3212836864
